# v30 with the whole instruction stream shifted by 4 bytes (one s_nop at entry): code-placement phase
# speedup vs baseline: 1.0049x; 1.0049x over previous
; #define LAS __attribute__((address_space(3)))
; __global__ void __launch_bounds__(NWAVES * 64, 2) fwd_kernel(Args args) {
;     extern __shared__ __attribute__((aligned(16))) unsigned char lds_raw[];
;     LAS unsigned char* lds = (LAS unsigned char*)lds_raw;
;     cg::grid_group cgrid = cg::this_grid();
;     if (threadIdx.x < 2) ((volatile LAS unsigned*)(lds + XB_LDS_OFF))[threadIdx.x] = 0u;
;     __syncthreads();
;     XcdBarrier xbar;
;     struct GridSeam { XcdBarrier* b; __device__ __forceinline__ void sync() const { xcd_barrier(*b); } } grid{&xbar};
;     const int G = gridDim.x, bx = blockIdx.x;
;     const int vcu = (G % 8 == 0) ? (bx % 8) * (G / 8) + bx / 8 : bx;
_Z10fwd_kernel4Args:
	s_load_dwordx2 s[82:83], s[0:1], 0x3d8
	s_load_dword s85, s[0:1], 0x3e0
	s_add_u32 s12, s0, 0x3d8
	v_and_b32_e32 v242, 0x3ff, v0
	s_mov_b32 s80, s2
	s_nop 0
	s_addc_u32 s13, s1, 0
	v_cmp_gt_u32_e32 vcc, 2, v242
	s_and_saveexec_b64 s[4:5], vcc
	v_lshl_add_u32 v1, v242, 2, 0
	v_add_u32_e32 v1, 0x20400, v1
	v_mov_b32_e32 v2, 0
	ds_write_b32 v1, v2
	s_or_b64 exec, exec, s[4:5]
	s_waitcnt lgkmcnt(0)
	s_and_b32 s2, s82, 7
	s_cmp_lg_u32 s2, 0
	s_mov_b32 s92, s80
	s_barrier
	s_cbranch_scc1 .LBB0_4
	s_ashr_i32 s3, s80, 31
	s_lshr_b32 s3, s3, 29
	s_add_i32 s3, s80, s3
	s_and_b32 s4, s3, -8
	s_ashr_i32 s2, s82, 3
	s_sub_i32 s4, s80, s4
	s_mul_i32 s2, s2, s4
	s_ashr_i32 s3, s3, 3
	s_add_i32 s92, s2, s3
